# attention: q of the next unit's first tile requested during the last tile, sink kept across units; unit start no longer waits behind the next unit's K/V loads
# speedup vs baseline: 1.0794x; 1.0008x over previous
; #define LAS __attribute__((address_space(3)))
; __device__ __forceinline__ void attn_phase(LAS unsigned char* lds, const bf16_t* QKVZ, const float* sinks, bf16_t* OG, int G, int bid, int tid) {
;     const int wave = __builtin_amdgcn_readfirstlane(tid >> 6), lane = tid & 63, fr = lane & 15, fq = lane >> 4;
;     constexpr int KP = 144, VP = 528;
;     LAS unsigned char* Kl = lds; LAS unsigned char* Vt = lds + 256 * KP;
;     u32x4 pkv[4], pvv[4];
;     ...
;     if (bid < 1024) ATT_LOAD(bid);
;     for (int unit = bid; unit < 1024; unit += G) {
;         const int kvh = unit & 3, n = (unit >> 2) & 31, b = unit >> 7;
;         __syncthreads();
; #pragma unroll
;         for (int i = 0; i < 4; ++i) {
;             const int c = tid + 512 * i, key = c >> 3, ch = c & 7;
;             const u32x4 kv = pkv[i], vv = pvv[i];
;             *(LAS u32x4*)(Kl + key * KP + ch * 16) = kv;
;             LAS unsigned short* vp = (LAS unsigned short*)(Vt + (ch * 8) * VP + ((key ^ (ch << 2)) * 2));
;             vp[0 * (VP / 2)] = (unsigned short)(vv.x & 0xffffu); vp[1 * (VP / 2)] = (unsigned short)(vv.x >> 16);
;             vp[2 * (VP / 2)] = (unsigned short)(vv.y & 0xffffu); vp[3 * (VP / 2)] = (unsigned short)(vv.y >> 16);
;             vp[4 * (VP / 2)] = (unsigned short)(vv.z & 0xffffu); vp[5 * (VP / 2)] = (unsigned short)(vv.z >> 16);
;             vp[6 * (VP / 2)] = (unsigned short)(vv.w & 0xffffu); vp[7 * (VP / 2)] = (unsigned short)(vv.w >> 16);
;         }
;         if (unit + G < 1024) ATT_LOAD(unit + G);
;         __syncthreads();
;         const int g = wave >> 1, qh = wave & 1, h = kvh * 4 + g;
;         const float sink2 = sinks[h] * 1.4426950408889634f;
;         for (int mt = 0; mt < 4; ++mt) {
;             const int qo0 = qh * 64 + mt * 16;
;             const size_t row = (size_t)(b * T + n * 128 + qo0 + fr);
;             const bf16_t* qp = QKVZ + row * ATT_IN + h * 64 + fq * 8;
;             const bf16x8 q0 = *(const bf16x8*)qp, q1 = *(const bf16x8*)(qp + 32);
;             const int kt0 = (qh * 4 + mt) < 6 ? (qh * 4 + mt) : 6;
;             f32x4 s[10];
; #pragma unroll
;             for (int kt = 0; kt < 10; ++kt) {
;                 const LAS unsigned char* kp = Kl + ((kt0 + kt) * 16 + fr) * KP + fq * 16;
;                 const bf16x8 k0 = *(const LAS bf16x8*)kp, k1 = *(const LAS bf16x8*)(kp + 64);
;                 f32x4 acc = (f32x4){0.f, 0.f, 0.f, 0.f};
.LBB0_234:
	s_or_b64 exec, exec, s[10:11]
	v_bfe_u32 v32, v34, 4, 2
	v_lshl_add_u64 v[74:75], s[4:5], 0, v[72:73]
	v_lshlrev_b32_e32 v72, 3, v32
	v_lshl_add_u32 v90, v32, 4, 0
	v_lshlrev_b32_e32 v76, 2, v32
	v_mbcnt_lo_u32_b32 v32, -1, 0
	v_and_b32_e32 v33, 7, v34
	v_mbcnt_hi_u32_b32 v32, -1, v32
	v_lshl_add_u32 v35, v33, 4, 0
	s_movk_i32 s8, 0x1070
	v_and_b32_e32 v38, 64, v32
	v_mad_u32_u24 v36, v33, s8, v35
	v_lshlrev_b32_e32 v37, 3, v33
	v_xor_b32_e32 v33, 16, v32
	v_add_u32_e32 v38, 64, v38
	v_and_b32_e32 v89, 15, v34
	v_cmp_lt_i32_e32 vcc, v33, v38
	v_lshrrev_b32_e32 v34, 1, v34
	v_and_b32_e32 v93, 4, v34
	v_cndmask_b32_e32 v33, v32, v33, vcc
	v_or_b32_e32 v34, 16, v89
	v_lshlrev_b32_e32 v91, 2, v33
	v_xor_b32_e32 v33, 32, v32
	v_lshrrev_b32_e32 v34, 1, v34
	v_cmp_lt_i32_e32 vcc, v33, v38
	v_and_b32_e32 v95, 12, v34
	v_or_b32_e32 v34, 32, v89
	v_cndmask_b32_e32 v32, v32, v33, vcc
	v_lshrrev_b32_e32 v34, 1, v34
	v_lshlrev_b32_e32 v92, 2, v32
	v_lshl_add_u64 v[32:33], s[0:1], 0, v[72:73]
	s_mov_b64 s[0:1], 0x4000000
	v_and_b32_e32 v96, 20, v34
	v_or_b32_e32 v34, 48, v89
	s_bfe_u32 s8, s12, 0x10006
	v_lshl_add_u64 v[78:79], v[32:33], 0, s[0:1]
	s_movk_i32 s19, 0x90
	v_lshlrev_b32_e32 v33, 1, v77
	v_lshlrev_b32_e32 v39, 1, v86
	v_lshlrev_b32_e32 v41, 1, v87
	v_lshlrev_b32_e32 v43, 1, v88
	v_lshrrev_b32_e32 v34, 1, v34
	s_lshl_b32 s10, s8, 6
	v_mul_lo_u32 v32, v77, s19
	v_xor_b32_e32 v33, v33, v37
	v_mul_lo_u32 v38, v86, s19
	v_xor_b32_e32 v39, v39, v37
	v_mul_lo_u32 v40, v87, s19
	v_xor_b32_e32 v41, v41, v37
	v_mul_lo_u32 v42, v88, s19
	v_xor_b32_e32 v37, v43, v37
	s_movk_i32 s0, 0x210
	v_and_b32_e32 v97, 28, v34
	v_sub_u32_e32 v34, v76, v89
	s_ashr_i32 s17, s12, 7
	s_lshl_b32 s18, s8, 2
	v_mad_u32_u24 v94, v89, s0, 0
	v_xor_b32_e32 v98, 0xffffffed, v76
	v_or_b32_e32 v99, s10, v89
	v_xor_b32_e32 v100, -3, v76
	v_xor_b32_e32 v101, 13, v76
	v_xor_b32_e32 v102, 29, v76
	v_xor_b32_e32 v103, 45, v76
	v_xor_b32_e32 v104, 61, v76
	v_xor_b32_e32 v105, 0x4d, v76
	v_xor_b32_e32 v106, 0x5d, v76
	v_xor_b32_e32 v107, 0x6d, v76
	v_xor_b32_e32 v108, 0xffffffee, v76
	v_xor_b32_e32 v109, -2, v76
	v_xor_b32_e32 v110, 14, v76
	v_xor_b32_e32 v111, 30, v76
	v_xor_b32_e32 v112, 46, v76
	v_xor_b32_e32 v113, 62, v76
	v_xor_b32_e32 v114, 0x4e, v76
	v_xor_b32_e32 v115, 0x5e, v76
	v_xor_b32_e32 v116, 0x6e, v76
	v_xor_b32_e32 v117, 0x7d, v76
	v_xor_b32_e32 v118, 0x7e, v76
	v_subrev_u32_e32 v119, s10, v34
	v_sub_u32_e32 v120, -16, v76
	v_sub_u32_e32 v121, 0, v76
	v_sub_u32_e32 v122, 16, v76
	v_sub_u32_e32 v123, 32, v76
	v_sub_u32_e32 v124, 48, v76
	v_sub_u32_e32 v125, 64, v76
	v_sub_u32_e32 v126, 0x50, v76
	v_sub_u32_e32 v127, 0x60, v76
	v_sub_u32_e32 v128, 0x70, v76
	s_movk_i32 s20, 0x80
	v_sub_u32_e32 v129, 0x80, v76
	s_lshl_b32 s21, s54, 5
	v_add_u32_e32 v130, v35, v32
	v_add_u32_e32 v131, v36, v33
	v_add_u32_e32 v132, v35, v38
	v_add_u32_e32 v133, v36, v39
	v_add_u32_e32 v134, v35, v40
	v_add_u32_e32 v135, v36, v41
	v_add_u32_e32 v136, v35, v42
	v_add_u32_e32 v137, v36, v37
	s_movk_i32 s22, 0x1400
	v_lshlrev_b32_e32 v72, 1, v72
	s_movk_i32 s23, 0xff7f
	v_mov_b32_e32 v138, 0xf149f2ca
	s_mov_b32 s12, s84
	s_mov_b32 s98, 0

; #define LAS __attribute__((address_space(3)))
; __device__ __forceinline__ void attn_phase(LAS unsigned char* lds, const bf16_t* QKVZ, const float* sinks, bf16_t* OG, int G, int bid, int tid) {
;     ...
;     for (int unit = bid; unit < 1024; unit += G) {
;         const int kvh = unit & 3, n = (unit >> 2) & 31, b = unit >> 7;
;         __syncthreads();
; #pragma unroll
;         for (int i = 0; i < 4; ++i) {
;             const int c = tid + 512 * i, key = c >> 3, ch = c & 7;
;             const u32x4 kv = pkv[i], vv = pvv[i];
;             *(LAS u32x4*)(Kl + key * KP + ch * 16) = kv;
;             LAS unsigned short* vp = (LAS unsigned short*)(Vt + (ch * 8) * VP + ((key ^ (ch << 2)) * 2));
;             vp[0 * (VP / 2)] = (unsigned short)(vv.x & 0xffffu); vp[1 * (VP / 2)] = (unsigned short)(vv.x >> 16);
;             vp[2 * (VP / 2)] = (unsigned short)(vv.y & 0xffffu); vp[3 * (VP / 2)] = (unsigned short)(vv.y >> 16);
;             vp[4 * (VP / 2)] = (unsigned short)(vv.z & 0xffffu); vp[5 * (VP / 2)] = (unsigned short)(vv.z >> 16);
;             vp[6 * (VP / 2)] = (unsigned short)(vv.w & 0xffffu); vp[7 * (VP / 2)] = (unsigned short)(vv.w >> 16);
;         }
;         if (unit + G < 1024) ATT_LOAD(unit + G);
;         __syncthreads();
;         const int g = wave >> 1, qh = wave & 1, h = kvh * 4 + g;
;         const float sink2 = sinks[h] * 1.4426950408889634f;
;         for (int mt = 0; mt < 4; ++mt) {
;             const int qo0 = qh * 64 + mt * 16;
;             const size_t row = (size_t)(b * T + n * 128 + qo0 + fr);
;             const bf16_t* qp = QKVZ + row * ATT_IN + h * 64 + fq * 8;
;             const bf16x8 q0 = *(const bf16x8*)qp, q1 = *(const bf16x8*)(qp + 32);
;             const int kt0 = (qh * 4 + mt) < 6 ? (qh * 4 + mt) : 6;
;             f32x4 s[10];
; #pragma unroll
;             for (int kt = 0; kt < 10; ++kt) {
;                 const LAS unsigned char* kp = Kl + ((kt0 + kt) * 16 + fr) * KP + fq * 16;
;                 const bf16x8 k0 = *(const LAS bf16x8*)kp, k1 = *(const LAS bf16x8*)(kp + 64);
;                 f32x4 acc = (f32x4){0.f, 0.f, 0.f, 0.f};
;                 acc = __builtin_amdgcn_mfma_f32_16x16x32_bf16(k0, q0, acc, 0, 0, 0);
;                 acc = __builtin_amdgcn_mfma_f32_16x16x32_bf16(k1, q1, acc, 0, 0, 0);
;                 s[kt] = acc;
;             }
.LBB0_245:
	s_lshl_b32 s1, s12, 2
	s_and_b32 s1, s1, 12
	s_bfe_u32 s0, s12, 0x50002
	s_add_i32 s12, s1, s17
	s_ashr_i32 s13, s12, 31
	s_and_b32 s8, s16, 0xfffff000
	s_lshl_b64 s[14:15], s[12:13], 2
	s_add_u32 s14, s6, s14
	s_addc_u32 s15, s7, s15
	s_waitcnt lgkmcnt(0)
	s_barrier
	s_cmp_lg_u32 s98, 0
	s_cbranch_scc1 .Lmy_att_nosink
	global_load_dword v32, v73, s[14:15]
.Lmy_att_nosink:
	s_lshl_b32 s14, s12, 6
	s_ashr_i32 s15, s14, 31
	s_cmp_lg_u32 s0, 0
	s_cselect_b64 s[12:13], -1, 0
	s_lshl_b64 s[14:15], s[14:15], 1
	v_or_b32_e32 v33, s8, v99
	v_lshl_add_u64 v[80:81], v[78:79], 0, s[14:15]
	s_add_u32 s14, s4, s14
	s_mov_b32 s1, 0
	v_mov_b32_e32 v139, v119
	v_lshl_or_b32 v140, s0, 7, v33
	s_addc_u32 s15, s5, s15
	s_mov_b32 s8, s18
	s_cmp_lg_u32 s98, 0
	s_cbranch_scc1 .Lmy_att_t0
	v_mov_b64_e32 v[194:195], s[14:15]
	v_mad_i64_i32 v[196:197], s[26:27], v140, s22, v[194:195]
	v_lshl_add_u64 v[194:195], v[196:197], 0, v[72:73]
	global_load_dwordx4 v[186:189], v[194:195], off
	global_load_dwordx4 v[190:193], v[194:195], off offset:64
	s_waitcnt vmcnt(0)
	v_mul_f32_e32 v141, 0x3fb8aa3b, v32
	s_cmp_eq_u32 s54, 0x100
	s_cselect_b32 s98, 1, 0
	s_branch .Lmy_att_t0
.LBB0_246:
	s_waitcnt vmcnt(4)
.Lmy_att_t0:
	v_add_u32_e32 v82, s1, v140
	v_mov_b64_e32 v[32:33], s[14:15]
	v_mad_i64_i32 v[84:85], s[26:27], v82, s22, v[32:33]
	v_lshl_add_u64 v[36:37], v[84:85], 0, v[72:73]
	v_mov_b64_e32 v[32:33], v[186:187]
	v_mov_b64_e32 v[34:35], v[188:189]
	v_mov_b64_e32 v[162:163], v[190:191]
	v_mov_b64_e32 v[164:165], v[192:193]
	s_mov_b32 s99, 0x14000
	s_cmp_eq_u32 s1, 48
	s_cselect_b32 s99, 0x27c4000, s99
	v_add_co_u32_e32 v194, vcc, s99, v36
	s_nop 1
	v_addc_co_u32_e32 v195, vcc, 0, v37, vcc
	global_load_dwordx4 v[186:189], v[194:195], off
	global_load_dwordx4 v[190:193], v[194:195], off offset:64
	v_lshlrev_b32_e32 v196, 1, v76
	v_mov_b32_e32 v197, v73
	v_lshl_add_u64 v[198:199], v[84:85], 0, v[196:197]
	global_load_dwordx2 v[200:201], v[198:199], off offset:3072
	global_load_dwordx2 v[202:203], v[198:199], off offset:3104
	global_load_dwordx2 v[204:205], v[198:199], off offset:3136
	global_load_dwordx2 v[206:207], v[198:199], off offset:3168
	s_min_u32 s25, s8, 6
	s_lshl_b32 s25, s25, 4
	v_or_b32_e32 v36, s25, v89
	v_mad_u32_u24 v40, v36, s19, v90
	ds_read_b128 v[36:39], v40
	ds_read_b128 v[40:43], v40 offset:64
	s_add_i32 s26, s25, 16
	s_add_i32 s29, s25, 32
	s_add_i32 s28, s25, 64
	s_add_i32 s27, s25, 0x60
	s_add_i32 s30, s25, 0x90
	v_subrev_u32_e32 v185, s25, v129
	v_add_u32_e32 v146, s25, v139
	v_subrev_u32_e32 v180, s25, v118
	v_subrev_u32_e32 v179, s25, v117
	v_subrev_u32_e32 v184, s25, v128
	v_subrev_u32_e32 v178, s25, v116
	v_subrev_u32_e32 v175, s25, v107
	v_subrev_u32_e32 v183, s25, v127
	v_subrev_u32_e32 v177, s25, v115
	v_subrev_u32_e32 v174, s25, v106
	v_subrev_u32_e32 v182, s25, v126
	v_subrev_u32_e32 v176, s25, v114
	v_subrev_u32_e32 v161, s25, v105
	v_subrev_u32_e32 v181, s25, v125
	v_subrev_u32_e32 v159, s25, v113
	v_subrev_u32_e32 v158, s25, v104
	v_subrev_u32_e32 v160, s25, v124
	v_subrev_u32_e32 v156, s25, v112
	v_subrev_u32_e32 v155, s25, v103
	v_subrev_u32_e32 v157, s25, v123
	v_subrev_u32_e32 v152, s25, v111
	v_subrev_u32_e32 v151, s25, v102
	v_subrev_u32_e32 v153, s25, v122
	v_subrev_u32_e32 v149, s25, v110
	v_subrev_u32_e32 v147, s25, v101
	v_subrev_u32_e32 v150, s25, v121
	v_subrev_u32_e32 v145, s25, v109
	v_subrev_u32_e32 v144, s25, v100
	v_subrev_u32_e32 v148, s25, v120
	v_subrev_u32_e32 v143, s25, v108
	v_subrev_u32_e32 v142, s25, v98
	v_ashrrev_i32_e32 v83, 31, v82
	v_add_u32_e32 v139, -16, v139
	s_waitcnt lgkmcnt(1)
	v_mfma_f32_16x16x32_bf16 v[36:39], v[36:39], v[32:35], 0
	s_waitcnt lgkmcnt(0)
	v_mfma_f32_16x16x32_bf16 v[68:71], v[40:43], v[162:165], v[36:39]
	s_nop 5
	v_or_b32_e32 v36, s26, v89
	v_mad_u32_u24 v40, v36, s19, v90
	ds_read_b128 v[36:39], v40
	ds_read_b128 v[40:43], v40 offset:64
	s_waitcnt lgkmcnt(1)
	v_mfma_f32_16x16x32_bf16 v[36:39], v[36:39], v[32:35], 0
	s_add_i32 s26, s25, 48
	s_waitcnt lgkmcnt(0)
	v_mfma_f32_16x16x32_bf16 v[64:67], v[40:43], v[162:165], v[36:39]
	s_nop 4
	v_or_b32_e32 v36, s29, v89
	v_mad_u32_u24 v40, v36, s19, v90
	ds_read_b128 v[36:39], v40
	ds_read_b128 v[40:43], v40 offset:64
	s_waitcnt lgkmcnt(1)
	v_mfma_f32_16x16x32_bf16 v[36:39], v[36:39], v[32:35], 0
	s_waitcnt lgkmcnt(0)
	v_mfma_f32_16x16x32_bf16 v[60:63], v[40:43], v[162:165], v[36:39]
	s_nop 5
	v_or_b32_e32 v36, s26, v89
	v_mad_u32_u24 v40, v36, s19, v90
	ds_read_b128 v[36:39], v40
	ds_read_b128 v[40:43], v40 offset:64
	s_waitcnt lgkmcnt(1)
	v_mfma_f32_16x16x32_bf16 v[36:39], v[36:39], v[32:35], 0
	s_add_i32 s26, s25, 0x50
	s_waitcnt lgkmcnt(0)
	v_mfma_f32_16x16x32_bf16 v[56:59], v[40:43], v[162:165], v[36:39]
	s_nop 4
	v_or_b32_e32 v36, s28, v89
	v_mad_u32_u24 v40, v36, s19, v90
	ds_read_b128 v[36:39], v40
	ds_read_b128 v[40:43], v40 offset:64
	s_waitcnt lgkmcnt(1)
	v_mfma_f32_16x16x32_bf16 v[36:39], v[36:39], v[32:35], 0
	s_waitcnt lgkmcnt(0)
	v_mfma_f32_16x16x32_bf16 v[52:55], v[40:43], v[162:165], v[36:39]
	s_nop 5
	v_or_b32_e32 v36, s26, v89
	v_mad_u32_u24 v40, v36, s19, v90
	ds_read_b128 v[36:39], v40
	ds_read_b128 v[40:43], v40 offset:64
	s_waitcnt lgkmcnt(1)
	v_mfma_f32_16x16x32_bf16 v[36:39], v[36:39], v[32:35], 0
	s_add_i32 s26, s25, 0x70
	s_waitcnt lgkmcnt(0)
	v_mfma_f32_16x16x32_bf16 v[48:51], v[40:43], v[162:165], v[36:39]
	s_nop 4
	v_or_b32_e32 v36, s27, v89
	v_mad_u32_u24 v40, v36, s19, v90
	ds_read_b128 v[36:39], v40
	ds_read_b128 v[40:43], v40 offset:64
	s_waitcnt lgkmcnt(1)
	v_mfma_f32_16x16x32_bf16 v[36:39], v[36:39], v[32:35], 0
	s_waitcnt lgkmcnt(0)
; #define LAS __attribute__((address_space(3)))
; __device__ __forceinline__ void attn_phase(LAS unsigned char* lds, const bf16_t* QKVZ, const float* sinks, bf16_t* OG, int G, int bid, int tid) {
;     ...
;             for (int kt = 0; kt < 10; ++kt) {
;                 const LAS unsigned char* kp = Kl + ((kt0 + kt) * 16 + fr) * KP + fq * 16;
;                 const bf16x8 k0 = *(const LAS bf16x8*)kp, k1 = *(const LAS bf16x8*)(kp + 64);
;                 f32x4 acc = (f32x4){0.f, 0.f, 0.f, 0.f};
;                 acc = __builtin_amdgcn_mfma_f32_16x16x32_bf16(k0, q0, acc, 0, 0, 0);
;                 acc = __builtin_amdgcn_mfma_f32_16x16x32_bf16(k1, q1, acc, 0, 0, 0);
;                 s[kt] = acc;
;             }
;             const int qi = 128 + qo0 + fr;
;             float mx = sink2;
; #pragma unroll
;             for (int kt = 0; kt < 10; ++kt)
; #pragma unroll
;                 for (int r = 0; r < 4; ++r) { const int si = (kt0 + kt) * 16 + 4 * fq + r, df = qi - si; const bool ok = (df >= 0) && (df < 128) && (n > 0 || si >= 128);
;                     const float v = ok ? s[kt][r] : -1e30f; s[kt][r] = v; mx = fmaxf(mx, v); }
	v_mfma_f32_16x16x32_bf16 v[44:47], v[40:43], v[162:165], v[36:39]
	s_nop 5
	v_or_b32_e32 v36, s26, v89
	v_mad_u32_u24 v40, v36, s19, v90
	ds_read_b128 v[36:39], v40
	ds_read_b128 v[40:43], v40 offset:64
	s_waitcnt lgkmcnt(1)
	v_mfma_f32_16x16x32_bf16 v[36:39], v[36:39], v[32:35], 0
	s_or_b32 s26, s25, 0x80
	s_waitcnt lgkmcnt(0)
	v_mfma_f32_16x16x32_bf16 v[40:43], v[40:43], v[162:165], v[36:39]
	s_nop 4
	v_or_b32_e32 v36, s26, v89
	v_mad_u32_u24 v154, v36, s19, v90
	ds_read_b128 v[36:39], v154
	ds_read_b128 v[166:169], v154 offset:64
	s_waitcnt lgkmcnt(1)
	v_mfma_f32_16x16x32_bf16 v[36:39], v[36:39], v[32:35], 0
	v_or_b32_e32 v154, s30, v89
	v_mad_u32_u24 v154, v154, s19, v90
	s_waitcnt lgkmcnt(0)
	v_mfma_f32_16x16x32_bf16 v[36:39], v[166:169], v[162:165], v[36:39]
	ds_read_b128 v[166:169], v154
	ds_read_b128 v[170:173], v154 offset:64
	v_or_b32_e32 v154, s25, v76
	s_waitcnt lgkmcnt(1)
	v_mfma_f32_16x16x32_bf16 v[32:35], v[166:169], v[32:35], 0
	s_waitcnt lgkmcnt(0)
	v_mfma_f32_16x16x32_bf16 v[32:35], v[170:173], v[162:165], v[32:35]
	v_add_u32_e32 v162, s1, v99
	v_add_u32_e32 v163, v162, v185
	v_cmp_gt_u32_e32 vcc, s20, v163
	s_and_b64 vcc, s[12:13], vcc
	v_add_u32_e32 v163, 0xffffff80, v146
	v_cndmask_b32_e32 v68, v138, v68, vcc
	v_cmp_lt_u32_e32 vcc, s23, v163
	s_and_b64 vcc, s[12:13], vcc
	v_add_u32_e32 v164, v162, v180
	v_cndmask_b32_e32 v69, v138, v69, vcc
	v_cmp_gt_u32_e32 vcc, s20, v164
	s_and_b64 vcc, s[12:13], vcc
	v_add_u32_e32 v164, v162, v179
	v_cndmask_b32_e32 v70, v138, v70, vcc
	v_cmp_gt_u32_e32 vcc, s20, v164
	s_and_b64 vcc, s[12:13], vcc
	v_add_u32_e32 v164, v162, v184
	v_cndmask_b32_e32 v71, v138, v71, vcc
	v_cmp_gt_u32_e32 vcc, s20, v164
	s_and_b64 vcc, s[12:13], vcc
	v_add_u32_e32 v164, 0xffffff90, v146
	v_cndmask_b32_e32 v64, v138, v64, vcc
	v_cmp_lt_u32_e32 vcc, s23, v164
	s_and_b64 vcc, s[12:13], vcc
	v_add_u32_e32 v164, v162, v178
	v_cndmask_b32_e32 v65, v138, v65, vcc
	v_cmp_gt_u32_e32 vcc, s20, v164
	s_and_b64 vcc, s[12:13], vcc
	v_add_u32_e32 v164, v162, v175
	v_cndmask_b32_e32 v66, v138, v66, vcc
	v_cmp_gt_u32_e32 vcc, s20, v164
	s_and_b64 vcc, s[12:13], vcc
	s_cmp_gt_u32 s8, 5
	v_add_u32_e32 v165, v162, v183
	s_cselect_b64 s[30:31], -1, 0
	v_cndmask_b32_e32 v67, v138, v67, vcc
	v_cmp_gt_u32_e32 vcc, s20, v165
	s_or_b64 s[30:31], s[12:13], s[30:31]
	s_and_b64 vcc, vcc, s[30:31]
	v_add_u32_e32 v165, 0xffffffa0, v146
	v_cndmask_b32_e32 v60, v138, v60, vcc
	v_cmp_lt_u32_e32 vcc, s23, v165
	s_and_b64 vcc, vcc, s[30:31]
	v_add_u32_e32 v165, v162, v177
	v_cndmask_b32_e32 v61, v138, v61, vcc
	v_cmp_gt_u32_e32 vcc, s20, v165
	s_and_b64 vcc, vcc, s[30:31]
	v_add_u32_e32 v165, v162, v174
	v_cndmask_b32_e32 v62, v138, v62, vcc
	v_cmp_gt_u32_e32 vcc, s20, v165
	s_and_b64 vcc, vcc, s[30:31]
	s_cmp_gt_u32 s8, 4
	v_add_u32_e32 v165, v162, v182
	s_cselect_b64 s[30:31], -1, 0
	v_cndmask_b32_e32 v63, v138, v63, vcc
	v_cmp_gt_u32_e32 vcc, s20, v165
	s_or_b64 s[30:31], s[12:13], s[30:31]
	s_and_b64 vcc, vcc, s[30:31]
	v_add_u32_e32 v165, 0xffffffb0, v146
	v_cndmask_b32_e32 v56, v138, v56, vcc
	v_cmp_lt_u32_e32 vcc, s23, v165
	s_and_b64 vcc, vcc, s[30:31]
	v_add_u32_e32 v165, v162, v176
	v_cndmask_b32_e32 v57, v138, v57, vcc
	v_cmp_gt_u32_e32 vcc, s20, v165
	s_and_b64 vcc, vcc, s[30:31]
	v_add_u32_e32 v161, v162, v161
	v_cndmask_b32_e32 v58, v138, v58, vcc
	v_cmp_gt_u32_e32 vcc, s20, v161
	s_and_b64 vcc, vcc, s[30:31]
	s_cmp_gt_u32 s8, 3
	v_add_u32_e32 v165, v162, v181
	s_cselect_b64 s[30:31], -1, 0
	v_cndmask_b32_e32 v59, v138, v59, vcc
	v_cmp_gt_u32_e32 vcc, s20, v165
	s_or_b64 s[30:31], s[12:13], s[30:31]
	s_and_b64 vcc, vcc, s[30:31]
	v_subrev_u32_e32 v165, 64, v146
	v_cndmask_b32_e32 v52, v138, v52, vcc
	v_cmp_lt_u32_e32 vcc, s23, v165
	s_and_b64 vcc, vcc, s[30:31]
	v_add_u32_e32 v159, v162, v159
	v_cndmask_b32_e32 v53, v138, v53, vcc
	v_cmp_gt_u32_e32 vcc, s20, v159
	s_and_b64 vcc, vcc, s[30:31]
	v_add_u32_e32 v158, v162, v158
	v_cndmask_b32_e32 v54, v138, v54, vcc
	v_cmp_gt_u32_e32 vcc, s20, v158
	s_and_b64 vcc, vcc, s[30:31]
	s_cmp_gt_u32 s8, 2
	v_add_u32_e32 v159, v162, v160
	s_cselect_b64 s[30:31], -1, 0
	v_cndmask_b32_e32 v55, v138, v55, vcc
	v_cmp_gt_u32_e32 vcc, s20, v159
	s_or_b64 s[30:31], s[12:13], s[30:31]
	s_and_b64 vcc, vcc, s[30:31]
	v_subrev_u32_e32 v159, 48, v146
	v_cndmask_b32_e32 v48, v138, v48, vcc
	v_cmp_lt_u32_e32 vcc, s23, v159
	s_and_b64 vcc, vcc, s[30:31]
	v_add_u32_e32 v156, v162, v156
	v_cndmask_b32_e32 v49, v138, v49, vcc
	v_cmp_gt_u32_e32 vcc, s20, v156
	s_and_b64 vcc, vcc, s[30:31]
	v_add_u32_e32 v155, v162, v155
	v_cndmask_b32_e32 v50, v138, v50, vcc
	v_cmp_gt_u32_e32 vcc, s20, v155
	s_and_b64 vcc, vcc, s[30:31]
	s_cmp_gt_u32 s8, 1
	v_add_u32_e32 v157, v162, v157
	s_cselect_b64 s[30:31], -1, 0
	v_cndmask_b32_e32 v51, v138, v51, vcc
	v_cmp_gt_u32_e32 vcc, s20, v157
	s_or_b64 s[30:31], s[12:13], s[30:31]
	s_and_b64 vcc, vcc, s[30:31]
	v_subrev_u32_e32 v157, 32, v146
	v_cndmask_b32_e32 v44, v138, v44, vcc
	v_cmp_lt_u32_e32 vcc, s23, v157
	s_and_b64 vcc, vcc, s[30:31]
	v_add_u32_e32 v152, v162, v152
	v_cndmask_b32_e32 v45, v138, v45, vcc
	v_cmp_gt_u32_e32 vcc, s20, v152
	s_and_b64 vcc, vcc, s[30:31]
	v_add_u32_e32 v151, v162, v151
	v_cndmask_b32_e32 v46, v138, v46, vcc
	v_cmp_gt_u32_e32 vcc, s20, v151
	v_max3_f32 v163, v141, v68, v69
	s_and_b64 vcc, vcc, s[30:31]
	s_or_b32 s30, s8, s0
	v_max3_f32 v163, v163, v70, v71
	v_add_u32_e32 v152, v162, v153
	s_cmp_lg_u32 s30, 0
	v_max3_f32 v163, v163, v64, v65
	v_cndmask_b32_e32 v47, v138, v47, vcc
	v_cmp_gt_u32_e32 vcc, s20, v152
	s_cselect_b64 s[30:31], -1, 0
	v_max3_f32 v163, v163, v66, v67
	s_and_b64 vcc, s[30:31], vcc
	v_add_u32_e32 v152, -16, v146
; __device__ __forceinline__ void attn_phase(LAS unsigned char* lds, const bf16_t* QKVZ, const float* sinks, bf16_t* OG, int G, int bid, int tid) {
;     ...
;             for (int kt = 0; kt < 10; ++kt)
; #pragma unroll
;                 for (int r = 0; r < 4; ++r) { const int si = (kt0 + kt) * 16 + 4 * fq + r, df = qi - si; const bool ok = (df >= 0) && (df < 128) && (n > 0 || si >= 128);
;                     const float v = ok ? s[kt][r] : -1e30f; s[kt][r] = v; mx = fmaxf(mx, v); }
;             mx = fmaxf(mx, __shfl_xor(mx, 16)); mx = fmaxf(mx, __shfl_xor(mx, 32));
;             float sum = 0.f;
; #pragma unroll
;             for (int kt = 0; kt < 10; ++kt)
; #pragma unroll
;                 for (int r = 0; r < 4; ++r) { const float p = __builtin_amdgcn_exp2f(s[kt][r] - mx); s[kt][r] = p; sum += p; }
;             sum += __shfl_xor(sum, 16); sum += __shfl_xor(sum, 32);
;             sum += __builtin_amdgcn_exp2f(sink2 - mx);
;             const float inv = 1.0f / sum;
	v_max3_f32 v163, v163, v60, v61
	v_cndmask_b32_e32 v40, v138, v40, vcc
	v_cmp_lt_u32_e32 vcc, s23, v152
	v_max3_f32 v163, v163, v62, v63
	s_and_b64 vcc, s[30:31], vcc
	v_add_u32_e32 v149, v162, v149
	v_max3_f32 v163, v163, v56, v57
	v_cndmask_b32_e32 v41, v138, v41, vcc
	v_cmp_gt_u32_e32 vcc, s20, v149
	v_max3_f32 v161, v163, v58, v59
	s_and_b64 vcc, s[30:31], vcc
	v_add_u32_e32 v147, v162, v147
	v_max3_f32 v161, v161, v52, v53
	v_cndmask_b32_e32 v42, v138, v42, vcc
	v_cmp_gt_u32_e32 vcc, s20, v147
	v_max3_f32 v158, v161, v54, v55
	s_and_b64 vcc, s[30:31], vcc
	v_add_u32_e32 v150, v162, v150
	v_max3_f32 v158, v158, v48, v49
	v_cndmask_b32_e32 v43, v138, v43, vcc
	v_cmp_gt_u32_e32 vcc, s20, v150
	v_max3_f32 v155, v158, v50, v51
	v_add_u32_e32 v145, v162, v145
	v_cndmask_b32_e32 v36, v138, v36, vcc
	v_cmp_lt_u32_e32 vcc, s23, v146
	v_max3_f32 v155, v155, v44, v45
	v_add_u32_e32 v144, v162, v144
	v_cndmask_b32_e32 v37, v138, v37, vcc
	v_cmp_gt_u32_e32 vcc, s20, v145
	v_max3_f32 v151, v155, v46, v47
	v_add_u32_e32 v145, v162, v148
	v_cndmask_b32_e32 v38, v138, v38, vcc
	v_cmp_gt_u32_e32 vcc, s20, v144
	v_max3_f32 v151, v151, v40, v41
	v_max3_f32 v147, v151, v42, v43
	v_cndmask_b32_e32 v39, v138, v39, vcc
	v_cmp_gt_u32_e32 vcc, s20, v145
	v_add_u32_e32 v145, 16, v146
	v_add_u32_e32 v143, v162, v143
	v_cndmask_b32_e32 v32, v138, v32, vcc
	v_cmp_lt_u32_e32 vcc, s23, v145
	v_max3_f32 v147, v147, v36, v37
	v_add_u32_e32 v142, v162, v142
	v_cndmask_b32_e32 v33, v138, v33, vcc
	v_cmp_gt_u32_e32 vcc, s20, v143
	v_max3_f32 v144, v147, v38, v39
	v_max3_f32 v144, v144, v32, v33
	v_cndmask_b32_e32 v34, v138, v34, vcc
	v_cmp_gt_u32_e32 vcc, s20, v142
	v_or_b32_e32 v164, s29, v76
	v_or_b32_e32 v163, s28, v76
	v_cndmask_b32_e32 v35, v138, v35, vcc
	v_max3_f32 v142, v144, v34, v35
	ds_bpermute_b32 v143, v91, v142
	v_or_b32_e32 v156, s27, v76
	v_or_b32_e32 v149, s26, v76
	s_add_i32 s1, s1, 16
	s_add_i32 s8, s8, 1
	s_waitcnt lgkmcnt(0)
	v_max_f32_e32 v143, v143, v143
	v_max_f32_e32 v142, v142, v143
	ds_bpermute_b32 v143, v92, v142
	s_cmp_eq_u32 s1, 64
	s_waitcnt lgkmcnt(0)
	v_max_f32_e32 v143, v143, v143
	v_max_f32_e32 v142, v142, v143
	v_sub_f32_e32 v68, v68, v142
	v_exp_f32_e32 v68, v68
	v_sub_f32_e32 v69, v69, v142
	v_exp_f32_e32 v69, v69
	v_sub_f32_e32 v70, v70, v142
	v_exp_f32_e32 v70, v70
	v_sub_f32_e32 v71, v71, v142
	v_exp_f32_e32 v71, v71
	v_sub_f32_e32 v64, v64, v142
	v_add_f32_e32 v143, 0, v68
	v_exp_f32_e32 v64, v64
	v_sub_f32_e32 v65, v65, v142
	v_add_f32_e32 v143, v69, v143
	v_exp_f32_e32 v65, v65
	v_sub_f32_e32 v66, v66, v142
	v_add_f32_e32 v143, v70, v143
	v_exp_f32_e32 v66, v66
	v_sub_f32_e32 v67, v67, v142
	v_add_f32_e32 v143, v71, v143
	v_exp_f32_e32 v67, v67
	v_sub_f32_e32 v60, v60, v142
	v_add_f32_e32 v143, v64, v143
	v_exp_f32_e32 v60, v60
	v_sub_f32_e32 v61, v61, v142
	v_add_f32_e32 v143, v65, v143
	v_exp_f32_e32 v61, v61
	v_sub_f32_e32 v62, v62, v142
	v_add_f32_e32 v143, v66, v143
	v_exp_f32_e32 v62, v62
	v_sub_f32_e32 v63, v63, v142
	v_add_f32_e32 v143, v67, v143
	v_exp_f32_e32 v63, v63
	v_sub_f32_e32 v56, v56, v142
	v_add_f32_e32 v143, v60, v143
	v_exp_f32_e32 v56, v56
	v_sub_f32_e32 v57, v57, v142
	v_add_f32_e32 v143, v61, v143
	v_exp_f32_e32 v57, v57
	v_sub_f32_e32 v58, v58, v142
	v_add_f32_e32 v143, v62, v143
	v_exp_f32_e32 v58, v58
	v_sub_f32_e32 v59, v59, v142
	v_add_f32_e32 v143, v63, v143
	v_exp_f32_e32 v59, v59
	v_sub_f32_e32 v52, v52, v142
	v_add_f32_e32 v143, v56, v143
	v_exp_f32_e32 v144, v52
	v_add_f32_e32 v143, v57, v143
	v_add_f32_e32 v143, v58, v143
	v_add_f32_e32 v143, v59, v143
	v_sub_f32_e32 v53, v53, v142
	v_add_f32_e32 v52, v144, v143
	v_exp_f32_e32 v143, v53
	v_sub_f32_e32 v53, v54, v142
	v_exp_f32_e32 v145, v53
	v_sub_f32_e32 v53, v55, v142
	v_exp_f32_e32 v146, v53
	v_sub_f32_e32 v48, v48, v142
	v_exp_f32_e32 v147, v48
	v_sub_f32_e32 v49, v49, v142
	v_add_f32_e32 v52, v143, v52
	v_exp_f32_e32 v148, v49
	v_sub_f32_e32 v49, v50, v142
	v_add_f32_e32 v52, v145, v52
	v_exp_f32_e32 v150, v49
	v_sub_f32_e32 v49, v51, v142
	v_add_f32_e32 v52, v146, v52
	v_exp_f32_e32 v151, v49
	v_sub_f32_e32 v44, v44, v142
	v_add_f32_e32 v48, v147, v52
	v_exp_f32_e32 v152, v44
	v_sub_f32_e32 v45, v45, v142
	v_add_f32_e32 v48, v148, v48
	v_exp_f32_e32 v153, v45
	v_sub_f32_e32 v45, v46, v142
	v_add_f32_e32 v48, v150, v48
	v_exp_f32_e32 v155, v45
	v_sub_f32_e32 v45, v47, v142
	v_add_f32_e32 v48, v151, v48
	v_exp_f32_e32 v157, v45
	v_sub_f32_e32 v40, v40, v142
	v_add_f32_e32 v44, v152, v48
	v_exp_f32_e32 v158, v40
	v_sub_f32_e32 v41, v41, v142
	v_add_f32_e32 v44, v153, v44
	v_exp_f32_e32 v159, v41
	v_sub_f32_e32 v41, v42, v142
	v_add_f32_e32 v44, v155, v44
	v_exp_f32_e32 v160, v41
	v_sub_f32_e32 v41, v43, v142
	v_add_f32_e32 v44, v157, v44
	v_exp_f32_e32 v161, v41
	v_sub_f32_e32 v36, v36, v142
	v_add_f32_e32 v40, v158, v44
	v_exp_f32_e32 v162, v36
	v_sub_f32_e32 v37, v37, v142
	v_add_f32_e32 v40, v159, v40
	v_exp_f32_e32 v165, v37
	v_sub_f32_e32 v37, v38, v142
	v_add_f32_e32 v40, v160, v40
	v_exp_f32_e32 v166, v37
	v_sub_f32_e32 v37, v39, v142
	v_add_f32_e32 v40, v161, v40
	v_exp_f32_e32 v167, v37
	v_sub_f32_e32 v32, v32, v142
	v_add_f32_e32 v36, v162, v40
	v_exp_f32_e32 v168, v32
	v_sub_f32_e32 v33, v33, v142
	v_add_f32_e32 v36, v165, v36
	v_exp_f32_e32 v169, v33
	v_sub_f32_e32 v33, v34, v142
	v_add_f32_e32 v36, v166, v36
	v_exp_f32_e32 v170, v33
	v_sub_f32_e32 v33, v35, v142
	v_add_f32_e32 v36, v167, v36
	v_exp_f32_e32 v171, v33
	v_add_f32_e32 v32, v168, v36
	v_add_f32_e32 v32, v169, v32
	v_add_f32_e32 v32, v170, v32
	v_add_f32_e32 v32, v171, v32
	ds_bpermute_b32 v33, v91, v32
	v_add_u32_e32 v50, 16, v154
	v_bitop3_b32 v36, s25, v93, v76 bitop3:0x36
	v_xor_b32_e32 v38, v50, v93
	v_bitop3_b32 v40, s25, v95, v76 bitop3:0x36
	s_waitcnt lgkmcnt(0)
; __device__ __forceinline__ u32x4 pack8(const f32x4 a, const f32x4 b) { u32x4 w; w.x = cvt_pk_bf16(a[0], a[1]); w.y = cvt_pk_bf16(a[2], a[3]); w.z = cvt_pk_bf16(b[0], b[1]); w.w = cvt_pk_bf16(b[2], b[3]); return w; }
; #define LAS __attribute__((address_space(3)))
; __device__ __forceinline__ void attn_phase(LAS unsigned char* lds, const bf16_t* QKVZ, const float* sinks, bf16_t* OG, int G, int bid, int tid) {
;     ...
;             sum += __shfl_xor(sum, 16); sum += __shfl_xor(sum, 32);
;             sum += __builtin_amdgcn_exp2f(sink2 - mx);
;             const float inv = 1.0f / sum;
;             f32x4 o[4];
; #pragma unroll
;             for (int dt = 0; dt < 4; ++dt) o[dt] = (f32x4){0.f, 0.f, 0.f, 0.f};
; #pragma unroll
;             for (int kk = 0; kk < 5; ++kk) {
;                 const u32x4 pw = pack8(s[2 * kk], s[2 * kk + 1]);
;                 const bf16x8 pf = __builtin_bit_cast(bf16x8, pw);
; #pragma unroll
;                 for (int dt = 0; dt < 4; ++dt) {
;                     const int d = dt * 16 + fr, sw = ((d >> 3) & 7) << 2, keyA = 16 * (kt0 + 2 * kk) + 4 * fq, keyB = keyA + 16;
;                     const u32x2 va = *(const LAS u32x2*)(Vt + d * VP + ((keyA ^ sw) * 2)), vb = *(const LAS u32x2*)(Vt + d * VP + ((keyB ^ sw) * 2));
;                     const u32x4 vw = (u32x4){va.x, va.y, vb.x, vb.y};
;                     o[dt] = __builtin_amdgcn_mfma_f32_16x16x32_bf16(__builtin_bit_cast(bf16x8, vw), pf, o[dt], 0, 0, 0);
;                 }
;             }
	v_add_f32_e32 v32, v32, v33
	ds_bpermute_b32 v33, v92, v32
	v_xor_b32_e32 v42, v50, v95
	v_bitop3_b32 v44, s25, v96, v76 bitop3:0x36
	v_xor_b32_e32 v46, v50, v96
	v_bitop3_b32 v48, s25, v97, v76 bitop3:0x36
	s_waitcnt lgkmcnt(0)
	v_add_f32_e32 v32, v32, v33
	v_sub_f32_e32 v33, v141, v142
	v_exp_f32_e32 v33, v33
	v_xor_b32_e32 v50, v50, v97
	v_lshl_add_u32 v36, v36, 1, v94
	v_lshl_add_u32 v38, v38, 1, v94
	v_lshl_add_u32 v40, v40, 1, v94
	v_lshl_add_u32 v42, v42, 1, v94
	v_lshl_add_u32 v44, v44, 1, v94
	v_lshl_add_u32 v46, v46, 1, v94
	v_lshl_add_u32 v48, v48, 1, v94
	v_lshl_add_u32 v50, v50, 1, v94
	v_add_f32_e32 v142, v33, v32
	v_cvt_pk_bf16_f32 v32, v68, v69
	v_cvt_pk_bf16_f32 v33, v70, v71
	v_cvt_pk_bf16_f32 v34, v64, v65
	v_cvt_pk_bf16_f32 v35, v66, v67
	ds_read_b64 v[36:37], v36 offset:36864
	ds_read_b64 v[38:39], v38 offset:36864
	ds_read_b64 v[40:41], v40 offset:45312
	ds_read_b64 v[42:43], v42 offset:45312
	ds_read_b64 v[44:45], v44 offset:53760
	ds_read_b64 v[46:47], v46 offset:53760
	ds_read_b64 v[48:49], v48 offset:62208
	ds_read_b64 v[50:51], v50 offset:62208
	s_waitcnt lgkmcnt(6)
	v_mfma_f32_16x16x32_bf16 v[36:39], v[36:39], v[32:35], 0
	v_bitop3_b32 v52, s29, v93, v76 bitop3:0x36
	v_lshl_add_u32 v52, v52, 1, v94
	s_waitcnt lgkmcnt(4)
	v_mfma_f32_16x16x32_bf16 v[40:43], v[40:43], v[32:35], 0
	s_waitcnt lgkmcnt(2)
	v_mfma_f32_16x16x32_bf16 v[44:47], v[44:47], v[32:35], 0
	s_waitcnt lgkmcnt(0)
	v_mfma_f32_16x16x32_bf16 v[32:35], v[48:51], v[32:35], 0
	v_cvt_pk_bf16_f32 v48, v60, v61
	v_cvt_pk_bf16_f32 v49, v62, v63
	v_cvt_pk_bf16_f32 v50, v56, v57
	v_add_u32_e32 v56, 16, v164
	v_xor_b32_e32 v54, v56, v93
	v_lshl_add_u32 v54, v54, 1, v94
	v_cvt_pk_bf16_f32 v51, v58, v59
	ds_read_b64 v[52:53], v52 offset:36864
	ds_read_b64 v[54:55], v54 offset:36864
	s_waitcnt lgkmcnt(0)
	v_mfma_f32_16x16x32_bf16 v[36:39], v[52:55], v[48:51], v[36:39]
	v_bitop3_b32 v52, s29, v95, v76 bitop3:0x36
	v_xor_b32_e32 v54, v56, v95
	v_lshl_add_u32 v52, v52, 1, v94
	v_lshl_add_u32 v54, v54, 1, v94
	ds_read_b64 v[52:53], v52 offset:45312
	ds_read_b64 v[54:55], v54 offset:45312
	s_waitcnt lgkmcnt(0)
	v_mfma_f32_16x16x32_bf16 v[40:43], v[52:55], v[48:51], v[40:43]
	v_bitop3_b32 v52, s29, v96, v76 bitop3:0x36
	v_xor_b32_e32 v54, v56, v96
	v_lshl_add_u32 v52, v52, 1, v94
	v_lshl_add_u32 v54, v54, 1, v94
	ds_read_b64 v[52:53], v52 offset:53760
	ds_read_b64 v[54:55], v54 offset:53760
	s_waitcnt lgkmcnt(0)
	v_mfma_f32_16x16x32_bf16 v[44:47], v[52:55], v[48:51], v[44:47]
	v_bitop3_b32 v52, s29, v97, v76 bitop3:0x36
	v_xor_b32_e32 v54, v56, v97
	v_lshl_add_u32 v52, v52, 1, v94
	v_lshl_add_u32 v54, v54, 1, v94
	ds_read_b64 v[52:53], v52 offset:62208
	ds_read_b64 v[54:55], v54 offset:62208
	v_add_u32_e32 v56, 16, v163
	s_waitcnt lgkmcnt(0)
	v_mfma_f32_16x16x32_bf16 v[32:35], v[52:55], v[48:51], v[32:35]
	v_bitop3_b32 v52, s28, v93, v76 bitop3:0x36
	v_xor_b32_e32 v54, v56, v93
	v_lshl_add_u32 v52, v52, 1, v94
	v_lshl_add_u32 v54, v54, 1, v94
	v_cvt_pk_bf16_f32 v48, v144, v143
	v_cvt_pk_bf16_f32 v49, v145, v146
	v_cvt_pk_bf16_f32 v50, v147, v148
	v_cvt_pk_bf16_f32 v51, v150, v151
	ds_read_b64 v[52:53], v52 offset:36864
	ds_read_b64 v[54:55], v54 offset:36864
	s_waitcnt lgkmcnt(0)
	v_mfma_f32_16x16x32_bf16 v[36:39], v[52:55], v[48:51], v[36:39]
	v_bitop3_b32 v52, s28, v95, v76 bitop3:0x36
	v_xor_b32_e32 v54, v56, v95
	v_lshl_add_u32 v52, v52, 1, v94
	v_lshl_add_u32 v54, v54, 1, v94
	ds_read_b64 v[52:53], v52 offset:45312
	ds_read_b64 v[54:55], v54 offset:45312
	s_waitcnt lgkmcnt(0)
	v_mfma_f32_16x16x32_bf16 v[40:43], v[52:55], v[48:51], v[40:43]
	v_bitop3_b32 v52, s28, v96, v76 bitop3:0x36
	v_xor_b32_e32 v54, v56, v96
	v_lshl_add_u32 v52, v52, 1, v94
	v_lshl_add_u32 v54, v54, 1, v94
	ds_read_b64 v[52:53], v52 offset:53760
	ds_read_b64 v[54:55], v54 offset:53760
	s_waitcnt lgkmcnt(0)
	v_mfma_f32_16x16x32_bf16 v[44:47], v[52:55], v[48:51], v[44:47]
	v_bitop3_b32 v52, s28, v97, v76 bitop3:0x36
	v_xor_b32_e32 v54, v56, v97
	v_lshl_add_u32 v52, v52, 1, v94
	v_lshl_add_u32 v54, v54, 1, v94
	ds_read_b64 v[52:53], v52 offset:62208
	ds_read_b64 v[54:55], v54 offset:62208
	v_add_u32_e32 v56, 16, v156
	s_waitcnt lgkmcnt(0)
	v_mfma_f32_16x16x32_bf16 v[32:35], v[52:55], v[48:51], v[32:35]
	v_bitop3_b32 v52, s27, v93, v76 bitop3:0x36
	v_xor_b32_e32 v54, v56, v93
	v_lshl_add_u32 v52, v52, 1, v94
	v_lshl_add_u32 v54, v54, 1, v94
	v_cvt_pk_bf16_f32 v48, v152, v153
	v_cvt_pk_bf16_f32 v49, v155, v157
	v_cvt_pk_bf16_f32 v50, v158, v159
	v_cvt_pk_bf16_f32 v51, v160, v161
	ds_read_b64 v[52:53], v52 offset:36864
	ds_read_b64 v[54:55], v54 offset:36864
	s_waitcnt lgkmcnt(0)
	v_mfma_f32_16x16x32_bf16 v[36:39], v[52:55], v[48:51], v[36:39]
	v_bitop3_b32 v52, s27, v95, v76 bitop3:0x36
	v_xor_b32_e32 v54, v56, v95
	v_lshl_add_u32 v52, v52, 1, v94
	v_lshl_add_u32 v54, v54, 1, v94
	ds_read_b64 v[52:53], v52 offset:45312
	ds_read_b64 v[54:55], v54 offset:45312
	s_waitcnt lgkmcnt(0)
	v_mfma_f32_16x16x32_bf16 v[40:43], v[52:55], v[48:51], v[40:43]
	v_bitop3_b32 v52, s27, v96, v76 bitop3:0x36
	v_xor_b32_e32 v54, v56, v96
	v_lshl_add_u32 v52, v52, 1, v94
	v_lshl_add_u32 v54, v54, 1, v94
	ds_read_b64 v[52:53], v52 offset:53760
	ds_read_b64 v[54:55], v54 offset:53760
	s_waitcnt lgkmcnt(0)
	v_mfma_f32_16x16x32_bf16 v[52:55], v[52:55], v[48:51], v[44:47]
	s_nop 2
	v_bitop3_b32 v44, s27, v97, v76 bitop3:0x36
	v_xor_b32_e32 v46, v56, v97
	v_lshl_add_u32 v44, v44, 1, v94
	v_lshl_add_u32 v46, v46, 1, v94
	ds_read_b64 v[44:45], v44 offset:62208
	ds_read_b64 v[46:47], v46 offset:62208
	v_add_u32_e32 v56, 16, v149
	s_waitcnt lgkmcnt(0)
; __device__ __forceinline__ unsigned cvt_pk_bf16(float lo, float hi) { unsigned r; asm volatile("v_cvt_pk_bf16_f32 %0, %1, %2" : "=v"(r) : "v"(lo), "v"(hi)); return r; }
; __device__ __forceinline__ float bflo(unsigned w) { return __uint_as_float(w << 16); }
; __device__ __forceinline__ float bfhi(unsigned w) { return __uint_as_float(w & 0xffff0000u); }
; __device__ __forceinline__ float fsigmoid(float x) { return __builtin_amdgcn_rcpf(1.0f + __expf(-x)); }
; __device__ __forceinline__ u32x4 pack8(const f32x4 a, const f32x4 b) { u32x4 w; w.x = cvt_pk_bf16(a[0], a[1]); w.y = cvt_pk_bf16(a[2], a[3]); w.z = cvt_pk_bf16(b[0], b[1]); w.w = cvt_pk_bf16(b[2], b[3]); return w; }
; #define LAS __attribute__((address_space(3)))
; __device__ __forceinline__ void attn_phase(LAS unsigned char* lds, const bf16_t* QKVZ, const float* sinks, bf16_t* OG, int G, int bid, int tid) {
;     ...
;             for (int kk = 0; kk < 5; ++kk) {
;                 const u32x4 pw = pack8(s[2 * kk], s[2 * kk + 1]);
;                 const bf16x8 pf = __builtin_bit_cast(bf16x8, pw);
; #pragma unroll
;                 for (int dt = 0; dt < 4; ++dt) {
;                     const int d = dt * 16 + fr, sw = ((d >> 3) & 7) << 2, keyA = 16 * (kt0 + 2 * kk) + 4 * fq, keyB = keyA + 16;
;                     const u32x2 va = *(const LAS u32x2*)(Vt + d * VP + ((keyA ^ sw) * 2)), vb = *(const LAS u32x2*)(Vt + d * VP + ((keyB ^ sw) * 2));
;                     const u32x4 vw = (u32x4){va.x, va.y, vb.x, vb.y};
;                     o[dt] = __builtin_amdgcn_mfma_f32_16x16x32_bf16(__builtin_bit_cast(bf16x8, vw), pf, o[dt], 0, 0, 0);
;                 }
;             }
;             const bf16_t* zp = QKVZ + row * ATT_IN + 1536 + h * 64 + 4 * fq;
;             bf16_t* op = OG + row * D + h * 64 + 4 * fq;
; #pragma unroll
;             for (int dt = 0; dt < 4; ++dt) {
;                 const u32x2 zw = *(const u32x2*)(zp + dt * 16);
;                 const float z0 = bflo(zw.x), z1 = bfhi(zw.x), z2 = bflo(zw.y), z3 = bfhi(zw.y);
;                 const float r0 = o[dt][0] * inv * z0 * fsigmoid(z0), r1 = o[dt][1] * inv * z1 * fsigmoid(z1), r2 = o[dt][2] * inv * z2 * fsigmoid(z2), r3 = o[dt][3] * inv * z3 * fsigmoid(z3);
;                 u32x2 w; w.x = cvt_pk_bf16(r0, r1); w.y = cvt_pk_bf16(r2, r3);
;                 *(u32x2*)(op + dt * 16) = w;
;             }
;         }
	v_mfma_f32_16x16x32_bf16 v[32:35], v[44:47], v[48:51], v[32:35]
	v_bitop3_b32 v44, s26, v93, v76 bitop3:0x36
	v_xor_b32_e32 v46, v56, v93
	v_lshl_add_u32 v44, v44, 1, v94
	v_lshl_add_u32 v46, v46, 1, v94
	v_cvt_pk_bf16_f32 v48, v162, v165
	v_cvt_pk_bf16_f32 v49, v166, v167
	v_cvt_pk_bf16_f32 v50, v168, v169
	v_cvt_pk_bf16_f32 v51, v170, v171
	ds_read_b64 v[44:45], v44 offset:36864
	ds_read_b64 v[46:47], v46 offset:36864
	s_waitcnt lgkmcnt(0)
	v_mfma_f32_16x16x32_bf16 v[44:47], v[44:47], v[48:51], v[36:39]
	s_nop 2
	v_bitop3_b32 v36, s26, v95, v76 bitop3:0x36
	v_xor_b32_e32 v38, v56, v95
	v_lshl_add_u32 v36, v36, 1, v94
	v_lshl_add_u32 v38, v38, 1, v94
	ds_read_b64 v[36:37], v36 offset:45312
	ds_read_b64 v[38:39], v38 offset:45312
	s_waitcnt lgkmcnt(0)
	v_mfma_f32_16x16x32_bf16 v[40:43], v[36:39], v[48:51], v[40:43]
	v_bitop3_b32 v36, s26, v96, v76 bitop3:0x36
	v_xor_b32_e32 v38, v56, v96
	v_lshl_add_u32 v36, v36, 1, v94
	v_lshl_add_u32 v38, v38, 1, v94
	ds_read_b64 v[36:37], v36 offset:53760
	ds_read_b64 v[38:39], v38 offset:53760
	s_waitcnt lgkmcnt(0)
	v_mfma_f32_16x16x32_bf16 v[36:39], v[36:39], v[48:51], v[52:55]
	s_nop 2
	v_bitop3_b32 v52, s26, v97, v76 bitop3:0x36
	v_xor_b32_e32 v54, v56, v97
	v_lshl_add_u32 v52, v52, 1, v94
	v_lshl_add_u32 v54, v54, 1, v94
	ds_read_b64 v[52:53], v52 offset:62208
	ds_read_b64 v[54:55], v54 offset:62208
	s_waitcnt lgkmcnt(0)
	v_mfma_f32_16x16x32_bf16 v[32:35], v[52:55], v[48:51], v[32:35]
	v_div_scale_f32 v48, s[26:27], v142, v142, 1.0
	v_rcp_f32_e32 v49, v48
	s_nop 0
	v_fma_f32 v50, -v48, v49, 1.0
	v_fmac_f32_e32 v49, v50, v49
	v_div_scale_f32 v50, vcc, 1.0, v142, 1.0
	v_mul_f32_e32 v51, v50, v49
	v_fma_f32 v52, -v48, v51, v50
	v_fmac_f32_e32 v51, v52, v49
	v_fma_f32 v48, -v48, v51, v50
	v_div_fmas_f32 v48, v48, v49, v51
	v_div_fixup_f32 v52, v48, v142, 1.0
	v_lshlrev_b32_e32 v48, 1, v76
	v_mov_b32_e32 v49, v73
	v_lshl_add_u64 v[50:51], v[84:85], 0, v[48:49]
	v_mul_f32_e32 v44, v52, v44
	v_mul_f32_e32 v45, v52, v45
	v_mul_f32_e32 v46, v52, v46
	v_mul_f32_e32 v47, v52, v47
	v_lshlrev_b64 v[48:49], 11, v[82:83]
	v_lshl_add_u64 v[48:49], v[80:81], 0, v[48:49]
	v_mul_f32_e32 v41, v52, v41
	v_mul_f32_e32 v40, v52, v40
	v_mul_f32_e32 v42, v52, v42
	v_mul_f32_e32 v43, v52, v43
	v_mul_f32_e32 v37, v52, v37
	v_mul_f32_e32 v36, v52, v36
	v_mul_f32_e32 v38, v52, v38
	v_mul_f32_e32 v39, v52, v39
	v_mul_f32_e32 v33, v52, v33
	v_mul_f32_e32 v32, v52, v32
	v_mul_f32_e32 v34, v52, v34
	v_mul_f32_e32 v35, v52, v35
	s_waitcnt vmcnt(0)
	v_mov_b64_e32 v[54:55], v[200:201]
	v_lshlrev_b32_e32 v53, 16, v54
	v_mul_f32_e32 v44, v44, v53
	v_mul_f32_e32 v53, 0xbfb8aa3b, v53
	v_exp_f32_e32 v53, v53
	v_and_b32_e32 v54, 0xffff0000, v54
	v_lshlrev_b32_e32 v56, 16, v55
	v_mul_f32_e32 v45, v45, v54
	v_add_f32_e32 v53, 1.0, v53
	v_rcp_f32_e32 v53, v53
	v_and_b32_e32 v55, 0xffff0000, v55
	v_mul_f32_e32 v46, v46, v56
	v_mul_f32_e32 v47, v47, v55
	v_mul_f32_e32 v44, v44, v53
	v_mul_f32_e32 v53, 0xbfb8aa3b, v54
	v_exp_f32_e32 v53, v53
	s_nop 0
	v_add_f32_e32 v53, 1.0, v53
	v_rcp_f32_e32 v53, v53
	s_nop 0
	v_mul_f32_e32 v45, v45, v53
	v_mul_f32_e32 v53, 0xbfb8aa3b, v56
	v_exp_f32_e32 v53, v53
	v_cvt_pk_bf16_f32 v44, v44, v45
	s_nop 0
	v_add_f32_e32 v53, 1.0, v53
	v_rcp_f32_e32 v53, v53
	s_nop 0
	v_mul_f32_e32 v46, v46, v53
	v_mul_f32_e32 v53, 0xbfb8aa3b, v55
	v_exp_f32_e32 v53, v53
	s_nop 0
	v_add_f32_e32 v53, 1.0, v53
	v_rcp_f32_e32 v53, v53
	s_nop 0
	v_mul_f32_e32 v47, v47, v53
	v_cvt_pk_bf16_f32 v45, v46, v47
	global_store_dwordx2 v[48:49], v[44:45], off
	s_nop 1
	v_mov_b64_e32 v[44:45], v[202:203]
	v_lshlrev_b32_e32 v46, 16, v44
	v_and_b32_e32 v44, 0xffff0000, v44
	v_mul_f32_e32 v41, v41, v44
	v_mul_f32_e32 v44, 0xbfb8aa3b, v44
	v_exp_f32_e32 v44, v44
	v_lshlrev_b32_e32 v47, 16, v45
	v_and_b32_e32 v45, 0xffff0000, v45
	v_mul_f32_e32 v40, v40, v46
	v_add_f32_e32 v44, 1.0, v44
	v_rcp_f32_e32 v44, v44
	v_mul_f32_e32 v46, 0xbfb8aa3b, v46
	v_mul_f32_e32 v42, v42, v47
	v_exp_f32_e32 v46, v46
	v_mul_f32_e32 v41, v41, v44
	v_mul_f32_e32 v44, 0xbfb8aa3b, v47
	v_exp_f32_e32 v44, v44
	v_add_f32_e32 v46, 1.0, v46
	v_rcp_f32_e32 v46, v46
	v_mul_f32_e32 v43, v43, v45
	v_add_f32_e32 v44, 1.0, v44
	v_rcp_f32_e32 v44, v44
	v_mul_f32_e32 v40, v40, v46
	v_cvt_pk_bf16_f32 v40, v40, v41
	v_mul_f32_e32 v42, v42, v44
	v_mul_f32_e32 v44, 0xbfb8aa3b, v45
	v_exp_f32_e32 v44, v44
	s_nop 0
	v_add_f32_e32 v44, 1.0, v44
	v_rcp_f32_e32 v44, v44
	s_nop 0
	v_mul_f32_e32 v43, v43, v44
	v_cvt_pk_bf16_f32 v41, v42, v43
	global_store_dwordx2 v[48:49], v[40:41], off offset:32
	s_nop 1
	v_mov_b64_e32 v[40:41], v[204:205]
	v_lshlrev_b32_e32 v42, 16, v40
	v_and_b32_e32 v40, 0xffff0000, v40
	v_mul_f32_e32 v37, v37, v40
	v_mul_f32_e32 v40, 0xbfb8aa3b, v40
	v_exp_f32_e32 v40, v40
	v_lshlrev_b32_e32 v43, 16, v41
	v_and_b32_e32 v41, 0xffff0000, v41
	v_mul_f32_e32 v36, v36, v42
	v_add_f32_e32 v40, 1.0, v40
	v_rcp_f32_e32 v40, v40
	v_mul_f32_e32 v42, 0xbfb8aa3b, v42
	v_mul_f32_e32 v38, v38, v43
	v_exp_f32_e32 v42, v42
	v_mul_f32_e32 v37, v37, v40
	v_mul_f32_e32 v40, 0xbfb8aa3b, v43
	v_exp_f32_e32 v40, v40
	v_add_f32_e32 v42, 1.0, v42
	v_rcp_f32_e32 v42, v42
	v_mul_f32_e32 v39, v39, v41
	v_add_f32_e32 v40, 1.0, v40
	v_rcp_f32_e32 v40, v40
	v_mul_f32_e32 v36, v36, v42
	v_cvt_pk_bf16_f32 v36, v36, v37
	v_mul_f32_e32 v38, v38, v40
	v_mul_f32_e32 v40, 0xbfb8aa3b, v41
	v_exp_f32_e32 v40, v40
	s_nop 0
	v_add_f32_e32 v40, 1.0, v40
	v_rcp_f32_e32 v40, v40
	s_nop 0
	v_mul_f32_e32 v39, v39, v40
	v_cvt_pk_bf16_f32 v37, v38, v39
	global_store_dwordx2 v[48:49], v[36:37], off offset:64
	s_nop 1
	v_mov_b64_e32 v[36:37], v[206:207]
	v_lshlrev_b32_e32 v38, 16, v36
	v_and_b32_e32 v36, 0xffff0000, v36
	v_mul_f32_e32 v33, v33, v36
	v_mul_f32_e32 v36, 0xbfb8aa3b, v36
	v_exp_f32_e32 v36, v36
	v_lshlrev_b32_e32 v39, 16, v37
	v_and_b32_e32 v37, 0xffff0000, v37
	v_mul_f32_e32 v32, v32, v38
	v_add_f32_e32 v36, 1.0, v36
	v_rcp_f32_e32 v36, v36
	v_mul_f32_e32 v38, 0xbfb8aa3b, v38
	v_mul_f32_e32 v34, v34, v39
	v_exp_f32_e32 v38, v38
	v_mul_f32_e32 v33, v33, v36
	v_mul_f32_e32 v36, 0xbfb8aa3b, v39
	v_exp_f32_e32 v36, v36
	v_add_f32_e32 v38, 1.0, v38
	v_rcp_f32_e32 v38, v38
	v_mul_f32_e32 v35, v35, v37
	v_add_f32_e32 v36, 1.0, v36
	v_rcp_f32_e32 v36, v36
	v_mul_f32_e32 v32, v32, v38
	v_cvt_pk_bf16_f32 v32, v32, v33
	v_mul_f32_e32 v34, v34, v36
	v_mul_f32_e32 v36, 0xbfb8aa3b, v37
	v_exp_f32_e32 v36, v36
	s_nop 0
	v_add_f32_e32 v36, 1.0, v36
	v_rcp_f32_e32 v36, v36
	s_nop 0
	v_mul_f32_e32 v35, v35, v36
	v_cvt_pk_bf16_f32 v33, v34, v35
	global_store_dwordx2 v[48:49], v[32:33], off offset:96
	s_cbranch_scc0 .LBB0_246
	s_add_i32 s16, s16, s21
	s_and_b64 vcc, exec, s[10:11]
	s_mov_b32 s12, s24
	s_cbranch_vccz .LBB0_235
